# prologue S5 table: B rows of the thread requested before the discretisation math
# speedup vs baseline: 1.0010x; 1.0010x over previous
.LBB11_104:
	v_lshrrev_b32_e32 v14, 6, v10
	v_ashrrev_i32_e32 v15, 6, v10
	v_bfi_b32 v12, s25, v15, v14
	v_ashrrev_i32_e32 v13, 31, v12
	v_lshl_add_u64 v[12:13], v[12:13], 2, s[20:21]
	global_load_dword v8, v[12:13], off
	v_ashrrev_i32_e32 v11, 31, v10
	v_lshlrev_b64 v[16:17], 2, v[10:11]
	v_lshl_add_u64 v[12:13], s[18:19], 0, v[16:17]
	global_load_dword v13, v[12:13], off
	v_lshl_add_u64 v[16:17], s[16:17], 0, v[16:17]
	global_load_dword v12, v[16:17], off
	global_load_dword v250, v[6:7], off
	global_load_dword v250, v[4:5], off
	s_waitcnt vmcnt(4)
	v_mul_f32_e32 v16, 0x3fb8aa3b, v8
	v_fma_f32 v17, v8, s40, -v16
	v_rndne_f32_e32 v18, v16
	v_fmac_f32_e32 v17, 0x32a5705f, v8
	v_sub_f32_e32 v16, v16, v18
	v_add_f32_e32 v16, v16, v17
	v_cvt_i32_f32_e32 v18, v18
	v_exp_f32_e32 v16, v16
	v_cmp_ngt_f32_e32 vcc, s41, v8
	v_ldexp_f32 v16, v16, v18
	s_nop 0
	v_cndmask_b32_e32 v16, 0, v16, vcc
	v_cmp_nlt_f32_e32 vcc, s42, v8
	s_nop 1
	v_cndmask_b32_e32 v18, v21, v16, vcc
	s_waitcnt vmcnt(3)
	v_mul_f32_e32 v16, v18, v13
	v_and_b32_e32 v17, 0x7fffffff, v16
	v_lshrrev_b32_e32 v8, 23, v17
	v_and_b32_e32 v19, 0x7fffff, v17
	v_cmp_nlt_f32_e64 s[36:37], |v16|, s43
	v_add_u32_e32 v29, 0xffffff88, v8
	v_or_b32_e32 v28, 0x800000, v19
	s_and_saveexec_b64 s[8:9], s[36:37]
	s_xor_b64 s[38:39], exec, s[8:9]
	s_cbranch_execz .LBB11_106
	v_cmp_lt_u32_e32 vcc, 63, v29
	v_mad_u64_u32 v[30:31], s[12:13], v28, s44, 0
	s_nop 0
	v_cndmask_b32_e32 v8, 0, v24, vcc
	v_add_u32_e32 v8, v8, v29
	v_cmp_lt_u32_e64 s[8:9], 31, v8
	s_nop 1
	v_cndmask_b32_e64 v19, 0, v25, s[8:9]
	v_add_u32_e32 v8, v19, v8
	v_cmp_lt_u32_e64 s[10:11], 31, v8
	s_nop 1
	v_cndmask_b32_e64 v19, 0, v25, s[10:11]
	v_add_u32_e32 v19, v19, v8
	v_mov_b32_e32 v8, v31
	v_mad_u64_u32 v[32:33], s[12:13], v28, s45, v[8:9]
	v_mov_b32_e32 v8, v33
	v_mad_u64_u32 v[34:35], s[12:13], v28, s46, v[8:9]
	v_mov_b32_e32 v8, v35
	v_mad_u64_u32 v[36:37], s[12:13], v28, s47, v[8:9]
	v_mov_b32_e32 v8, v37
	v_mad_u64_u32 v[38:39], s[12:13], v28, s51, v[8:9]
	v_mov_b32_e32 v8, v39
	v_mad_u64_u32 v[40:41], s[12:13], v28, s56, v[8:9]
	v_mov_b32_e32 v8, v41
	v_mad_u64_u32 v[42:43], s[12:13], v28, s57, v[8:9]
	v_cndmask_b32_e32 v27, v40, v36, vcc
	v_cndmask_b32_e32 v8, v42, v38, vcc
	v_cndmask_b32_e32 v33, v43, v40, vcc
	v_cndmask_b32_e64 v31, v8, v27, s[8:9]
	v_cndmask_b32_e64 v8, v33, v8, s[8:9]
	v_cndmask_b32_e32 v33, v38, v34, vcc
	v_cndmask_b32_e64 v27, v27, v33, s[8:9]
	v_sub_u32_e32 v35, 32, v19
	v_cmp_eq_u32_e64 s[12:13], 0, v19
	v_cndmask_b32_e32 v19, v36, v32, vcc
	v_cndmask_b32_e64 v8, v8, v31, s[10:11]
	v_cndmask_b32_e64 v31, v31, v27, s[10:11]
	v_cndmask_b32_e64 v32, v33, v19, s[8:9]
	v_alignbit_b32 v37, v8, v31, v35
	v_cndmask_b32_e64 v27, v27, v32, s[10:11]
	v_cndmask_b32_e32 v30, v34, v30, vcc
	v_cndmask_b32_e64 v8, v37, v8, s[12:13]
	v_alignbit_b32 v33, v31, v27, v35
	v_cndmask_b32_e64 v19, v19, v30, s[8:9]
	v_cndmask_b32_e64 v31, v33, v31, s[12:13]
	v_bfe_u32 v37, v8, 29, 1
	v_cndmask_b32_e64 v19, v32, v19, s[10:11]
	v_alignbit_b32 v33, v8, v31, 30
	v_sub_u32_e32 v38, 0, v37
	v_alignbit_b32 v30, v27, v19, v35
	v_xor_b32_e32 v33, v33, v38
	v_cndmask_b32_e64 v27, v30, v27, s[12:13]
	v_alignbit_b32 v30, v31, v27, 30
	v_ffbh_u32_e32 v31, v33
	v_min_u32_e32 v31, 32, v31
	v_alignbit_b32 v19, v27, v19, 30
	v_xor_b32_e32 v30, v30, v38
	v_sub_u32_e32 v32, 31, v31
	v_xor_b32_e32 v19, v19, v38
	v_alignbit_b32 v33, v33, v30, v32
	v_alignbit_b32 v19, v30, v19, v32
	v_alignbit_b32 v27, v33, v19, 9
	v_ffbh_u32_e32 v30, v27
	v_min_u32_e32 v30, 32, v30
	v_lshrrev_b32_e32 v36, 29, v8
	v_not_b32_e32 v32, v30
	v_alignbit_b32 v19, v27, v19, v32
	v_lshlrev_b32_e32 v27, 31, v36
	v_or_b32_e32 v32, 0x33000000, v27
	v_add_lshl_u32 v30, v30, v31, 23
	v_lshrrev_b32_e32 v19, 9, v19
	v_sub_u32_e32 v30, v32, v30
	v_or_b32_e32 v27, 0.5, v27
	v_lshlrev_b32_e32 v31, 23, v31
	v_or_b32_e32 v19, v30, v19
	v_lshrrev_b32_e32 v30, 9, v33
	v_sub_u32_e32 v27, v27, v31
	v_or_b32_e32 v27, v30, v27
	v_mul_f32_e32 v30, 0x3fc90fda, v27
	v_fma_f32 v31, v27, s58, -v30
	v_fmac_f32_e32 v31, 0x33a22168, v27
	v_fmac_f32_e32 v31, 0x3fc90fda, v19
	v_lshrrev_b32_e32 v8, 30, v8
	v_add_f32_e32 v27, v30, v31
	v_add_u32_e32 v19, v37, v8
